# P5 state scan rewritten by hand: two adjacent elements per thread in one pass, dwordx2 loads via stepped scalar base, packed bf16 pairs stored as dwords (store-widening lever applied to P5)
# baseline (speedup 1.0000x reference)
; __device__ __forceinline__ unsigned cvtpk(float lo, float hi) { f32x2_t v = {lo, hi}; bf16x2_t b = __builtin_convertvector(v, bf16x2_t); return __builtin_bit_cast(unsigned, b); }
; __device__ __forceinline__ float lg2gamma(int h) { return log2f(1.0f - exp2f(-5.0f - (float)h)); }
; __global__ void __launch_bounds__(512, 2) mk_fwd(Args a) {
;     ...
;     if (IN(5)) {
;         for (int idx = bid * 512 + tid; idx < 16 * 16384; idx += G * 512) {
;             const int bh = idx >> 14, ed = idx & 16383, h = bh & 7;
;             const float lg = lg2gamma(h), gm = exp2f(lg), gC = exp2f(128.0f * lg);
;             float v[32];
; #pragma unroll
;             for (int n = 0; n < 32; ++n) v[n] = STATE[(size_t)(bh * 32 + n) * 16384 + ed];
;             float run = 0.f;
; #pragma unroll
;             for (int n = 0; n < 32; ++n) { SPREV[(size_t)(bh * 32 + n) * 16384 + ed] = (bf16_t)(cvtpk(gm * run, 0.f) & 0xffffu); run = run * gC + v[n]; }
;         }
.LBB0_1150:
	s_lshr_b32 s98, s87, 4
	s_and_b32 s99, s98, 7
	v_cvt_f32_ubyte0_e32 v9, s99
	v_sub_f32_e32 v122, 0xc0a00000, v9
	s_lshl_b32 s99, s98, 21
	s_add_u32 s100, s52, s99
	s_addc_u32 s101, s53, 0
	s_lshl_b32 s99, s98, 20
	s_add_u32 s98, s34, s99
	s_addc_u32 s99, s35, 0
	v_and_b32_e32 v8, 0x1fff, v4
	v_lshlrev_b32_e32 v10, 3, v8
	v_lshlrev_b32_e32 v11, 2, v8
	global_load_dwordx2 v[14:15], v10, s[100:101]
	s_add_u32 s100, s100, 0x10000
	s_addc_u32 s101, s101, 0
	global_load_dwordx2 v[16:17], v10, s[100:101]
	s_add_u32 s100, s100, 0x10000
	s_addc_u32 s101, s101, 0
	global_load_dwordx2 v[18:19], v10, s[100:101]
	s_add_u32 s100, s100, 0x10000
	s_addc_u32 s101, s101, 0
	global_load_dwordx2 v[20:21], v10, s[100:101]
	s_add_u32 s100, s100, 0x10000
	s_addc_u32 s101, s101, 0
	global_load_dwordx2 v[22:23], v10, s[100:101]
	s_add_u32 s100, s100, 0x10000
	s_addc_u32 s101, s101, 0
	global_load_dwordx2 v[24:25], v10, s[100:101]
	s_add_u32 s100, s100, 0x10000
	s_addc_u32 s101, s101, 0
	global_load_dwordx2 v[26:27], v10, s[100:101]
	s_add_u32 s100, s100, 0x10000
	s_addc_u32 s101, s101, 0
	global_load_dwordx2 v[28:29], v10, s[100:101]
	s_add_u32 s100, s100, 0x10000
	s_addc_u32 s101, s101, 0
	global_load_dwordx2 v[30:31], v10, s[100:101]
	s_add_u32 s100, s100, 0x10000
	s_addc_u32 s101, s101, 0
	global_load_dwordx2 v[32:33], v10, s[100:101]
	s_add_u32 s100, s100, 0x10000
	s_addc_u32 s101, s101, 0
	global_load_dwordx2 v[34:35], v10, s[100:101]
	s_add_u32 s100, s100, 0x10000
	s_addc_u32 s101, s101, 0
	global_load_dwordx2 v[36:37], v10, s[100:101]
	s_add_u32 s100, s100, 0x10000
	s_addc_u32 s101, s101, 0
	global_load_dwordx2 v[38:39], v10, s[100:101]
	s_add_u32 s100, s100, 0x10000
	s_addc_u32 s101, s101, 0
	global_load_dwordx2 v[40:41], v10, s[100:101]
	s_add_u32 s100, s100, 0x10000
	s_addc_u32 s101, s101, 0
	global_load_dwordx2 v[42:43], v10, s[100:101]
	s_add_u32 s100, s100, 0x10000
	s_addc_u32 s101, s101, 0
	global_load_dwordx2 v[44:45], v10, s[100:101]
	s_add_u32 s100, s100, 0x10000
	s_addc_u32 s101, s101, 0
	global_load_dwordx2 v[46:47], v10, s[100:101]
	s_add_u32 s100, s100, 0x10000
	s_addc_u32 s101, s101, 0
	global_load_dwordx2 v[48:49], v10, s[100:101]
	s_add_u32 s100, s100, 0x10000
	s_addc_u32 s101, s101, 0
	global_load_dwordx2 v[50:51], v10, s[100:101]
	s_add_u32 s100, s100, 0x10000
	s_addc_u32 s101, s101, 0
	global_load_dwordx2 v[52:53], v10, s[100:101]
	s_add_u32 s100, s100, 0x10000
	s_addc_u32 s101, s101, 0
	global_load_dwordx2 v[54:55], v10, s[100:101]
	s_add_u32 s100, s100, 0x10000
	s_addc_u32 s101, s101, 0
	global_load_dwordx2 v[56:57], v10, s[100:101]
	s_add_u32 s100, s100, 0x10000
	s_addc_u32 s101, s101, 0
	global_load_dwordx2 v[58:59], v10, s[100:101]
	s_add_u32 s100, s100, 0x10000
	s_addc_u32 s101, s101, 0
	global_load_dwordx2 v[60:61], v10, s[100:101]
	s_add_u32 s100, s100, 0x10000
	s_addc_u32 s101, s101, 0
	global_load_dwordx2 v[62:63], v10, s[100:101]
	s_add_u32 s100, s100, 0x10000
	s_addc_u32 s101, s101, 0
	global_load_dwordx2 v[64:65], v10, s[100:101]
	s_add_u32 s100, s100, 0x10000
	s_addc_u32 s101, s101, 0
	global_load_dwordx2 v[66:67], v10, s[100:101]
	s_add_u32 s100, s100, 0x10000
	s_addc_u32 s101, s101, 0
	global_load_dwordx2 v[68:69], v10, s[100:101]
	s_add_u32 s100, s100, 0x10000
	s_addc_u32 s101, s101, 0
	global_load_dwordx2 v[70:71], v10, s[100:101]
	s_add_u32 s100, s100, 0x10000
	s_addc_u32 s101, s101, 0
	global_load_dwordx2 v[72:73], v10, s[100:101]
	s_add_u32 s100, s100, 0x10000
	s_addc_u32 s101, s101, 0
	global_load_dwordx2 v[74:75], v10, s[100:101]
	v_cmp_gt_f32_e32 vcc, s7, v122
	s_nop 1
	v_cndmask_b32_e32 v2, 0, v5, vcc
	v_add_f32_e32 v2, v122, v2
	v_exp_f32_e32 v2, v2
	v_cndmask_b32_e32 v122, 0, v6, vcc
	v_ldexp_f32 v2, v2, v122
	v_sub_f32_e32 v2, 1.0, v2
	v_cmp_gt_f32_e32 vcc, s8, v2
	s_nop 1
	v_cndmask_b32_e64 v13, 0, 32, vcc
	v_ldexp_f32 v2, v2, v13
	v_log_f32_e32 v2, v2
	v_cndmask_b32_e32 v13, 0, v7, vcc
	v_sub_f32_e32 v2, v2, v13
	v_mul_f32_e32 v13, 0x43000000, v2
	v_cmp_gt_f32_e32 vcc, s7, v2
	s_nop 1
	v_cndmask_b32_e32 v103, 0, v5, vcc
	v_cndmask_b32_e32 v104, 0, v6, vcc
	v_cmp_gt_f32_e32 vcc, s7, v13
	v_add_f32_e32 v103, v2, v103
	v_exp_f32_e32 v103, v103
	v_cndmask_b32_e32 v13, 0, v5, vcc
	v_fmac_f32_e32 v13, 0x43000000, v2
	v_exp_f32_e32 v13, v13
	v_cndmask_b32_e32 v2, 0, v6, vcc
	v_ldexp_f32 v103, v103, v104
	v_ldexp_f32 v2, v13, v2
	v_mul_f32_e32 v76, 0, v103
	v_cvt_pk_bf16_f32 v78, v76, v76
	global_store_dword v11, v78, s[98:99]
	s_waitcnt vmcnt(0)
; __device__ __forceinline__ unsigned cvtpk(float lo, float hi) { f32x2_t v = {lo, hi}; bf16x2_t b = __builtin_convertvector(v, bf16x2_t); return __builtin_bit_cast(unsigned, b); }
; __device__ __forceinline__ float lg2gamma(int h) { return log2f(1.0f - exp2f(-5.0f - (float)h)); }
; __global__ void __launch_bounds__(512, 2) mk_fwd(Args a) {
;     ...
;             const int bh = idx >> 14, ed = idx & 16383, h = bh & 7;
;             const float lg = lg2gamma(h), gm = exp2f(lg), gC = exp2f(128.0f * lg);
;             float v[32];
; #pragma unroll
;             for (int n = 0; n < 32; ++n) v[n] = STATE[(size_t)(bh * 32 + n) * 16384 + ed];
;             float run = 0.f;
; #pragma unroll
;             for (int n = 0; n < 32; ++n) { SPREV[(size_t)(bh * 32 + n) * 16384 + ed] = (bf16_t)(cvtpk(gm * run, 0.f) & 0xffffu); run = run * gC + v[n]; }
	v_fmac_f32_e32 v14, 0, v2
	v_fmac_f32_e32 v15, 0, v2
	s_add_u32 s98, s98, 0x8000
	s_addc_u32 s99, s99, 0
	v_mul_f32_e32 v76, v103, v14
	v_mul_f32_e32 v77, v103, v15
	v_cvt_pk_bf16_f32 v79, v76, v77
	global_store_dword v11, v79, s[98:99]
	v_fmac_f32_e32 v16, v2, v14
	v_fmac_f32_e32 v17, v2, v15
	s_add_u32 s98, s98, 0x8000
	s_addc_u32 s99, s99, 0
	v_mul_f32_e32 v76, v103, v16
	v_mul_f32_e32 v77, v103, v17
	v_cvt_pk_bf16_f32 v78, v76, v77
	global_store_dword v11, v78, s[98:99]
	v_fmac_f32_e32 v18, v2, v16
	v_fmac_f32_e32 v19, v2, v17
	s_add_u32 s98, s98, 0x8000
	s_addc_u32 s99, s99, 0
	v_mul_f32_e32 v76, v103, v18
	v_mul_f32_e32 v77, v103, v19
	v_cvt_pk_bf16_f32 v79, v76, v77
	global_store_dword v11, v79, s[98:99]
	v_fmac_f32_e32 v20, v2, v18
	v_fmac_f32_e32 v21, v2, v19
	s_add_u32 s98, s98, 0x8000
	s_addc_u32 s99, s99, 0
	v_mul_f32_e32 v76, v103, v20
	v_mul_f32_e32 v77, v103, v21
	v_cvt_pk_bf16_f32 v78, v76, v77
	global_store_dword v11, v78, s[98:99]
	v_fmac_f32_e32 v22, v2, v20
	v_fmac_f32_e32 v23, v2, v21
	s_add_u32 s98, s98, 0x8000
	s_addc_u32 s99, s99, 0
	v_mul_f32_e32 v76, v103, v22
	v_mul_f32_e32 v77, v103, v23
	v_cvt_pk_bf16_f32 v79, v76, v77
	global_store_dword v11, v79, s[98:99]
	v_fmac_f32_e32 v24, v2, v22
	v_fmac_f32_e32 v25, v2, v23
	s_add_u32 s98, s98, 0x8000
	s_addc_u32 s99, s99, 0
	v_mul_f32_e32 v76, v103, v24
	v_mul_f32_e32 v77, v103, v25
	v_cvt_pk_bf16_f32 v78, v76, v77
	global_store_dword v11, v78, s[98:99]
	v_fmac_f32_e32 v26, v2, v24
	v_fmac_f32_e32 v27, v2, v25
	s_add_u32 s98, s98, 0x8000
	s_addc_u32 s99, s99, 0
	v_mul_f32_e32 v76, v103, v26
	v_mul_f32_e32 v77, v103, v27
	v_cvt_pk_bf16_f32 v79, v76, v77
	global_store_dword v11, v79, s[98:99]
	v_fmac_f32_e32 v28, v2, v26
	v_fmac_f32_e32 v29, v2, v27
	s_add_u32 s98, s98, 0x8000
	s_addc_u32 s99, s99, 0
	v_mul_f32_e32 v76, v103, v28
	v_mul_f32_e32 v77, v103, v29
	v_cvt_pk_bf16_f32 v78, v76, v77
	global_store_dword v11, v78, s[98:99]
	v_fmac_f32_e32 v30, v2, v28
	v_fmac_f32_e32 v31, v2, v29
	s_add_u32 s98, s98, 0x8000
	s_addc_u32 s99, s99, 0
	v_mul_f32_e32 v76, v103, v30
	v_mul_f32_e32 v77, v103, v31
	v_cvt_pk_bf16_f32 v79, v76, v77
	global_store_dword v11, v79, s[98:99]
	v_fmac_f32_e32 v32, v2, v30
	v_fmac_f32_e32 v33, v2, v31
	s_add_u32 s98, s98, 0x8000
	s_addc_u32 s99, s99, 0
	v_mul_f32_e32 v76, v103, v32
	v_mul_f32_e32 v77, v103, v33
	v_cvt_pk_bf16_f32 v78, v76, v77
	global_store_dword v11, v78, s[98:99]
	v_fmac_f32_e32 v34, v2, v32
	v_fmac_f32_e32 v35, v2, v33
	s_add_u32 s98, s98, 0x8000
	s_addc_u32 s99, s99, 0
	v_mul_f32_e32 v76, v103, v34
	v_mul_f32_e32 v77, v103, v35
	v_cvt_pk_bf16_f32 v79, v76, v77
	global_store_dword v11, v79, s[98:99]
	v_fmac_f32_e32 v36, v2, v34
	v_fmac_f32_e32 v37, v2, v35
	s_add_u32 s98, s98, 0x8000
	s_addc_u32 s99, s99, 0
	v_mul_f32_e32 v76, v103, v36
	v_mul_f32_e32 v77, v103, v37
	v_cvt_pk_bf16_f32 v78, v76, v77
	global_store_dword v11, v78, s[98:99]
	v_fmac_f32_e32 v38, v2, v36
	v_fmac_f32_e32 v39, v2, v37
	s_add_u32 s98, s98, 0x8000
	s_addc_u32 s99, s99, 0
	v_mul_f32_e32 v76, v103, v38
	v_mul_f32_e32 v77, v103, v39
	v_cvt_pk_bf16_f32 v79, v76, v77
	global_store_dword v11, v79, s[98:99]
	v_fmac_f32_e32 v40, v2, v38
	v_fmac_f32_e32 v41, v2, v39
	s_add_u32 s98, s98, 0x8000
	s_addc_u32 s99, s99, 0
	v_mul_f32_e32 v76, v103, v40
	v_mul_f32_e32 v77, v103, v41
	v_cvt_pk_bf16_f32 v78, v76, v77
	global_store_dword v11, v78, s[98:99]
	v_fmac_f32_e32 v42, v2, v40
	v_fmac_f32_e32 v43, v2, v41
	s_add_u32 s98, s98, 0x8000
	s_addc_u32 s99, s99, 0
	v_mul_f32_e32 v76, v103, v42
	v_mul_f32_e32 v77, v103, v43
	v_cvt_pk_bf16_f32 v79, v76, v77
	global_store_dword v11, v79, s[98:99]
	v_fmac_f32_e32 v44, v2, v42
	v_fmac_f32_e32 v45, v2, v43
	s_add_u32 s98, s98, 0x8000
	s_addc_u32 s99, s99, 0
; __device__ __forceinline__ unsigned cvtpk(float lo, float hi) { f32x2_t v = {lo, hi}; bf16x2_t b = __builtin_convertvector(v, bf16x2_t); return __builtin_bit_cast(unsigned, b); }
; __device__ __forceinline__ float lg2gamma(int h) { return log2f(1.0f - exp2f(-5.0f - (float)h)); }
; __global__ void __launch_bounds__(512, 2) mk_fwd(Args a) {
;     ...
;             const int bh = idx >> 14, ed = idx & 16383, h = bh & 7;
;             const float lg = lg2gamma(h), gm = exp2f(lg), gC = exp2f(128.0f * lg);
;             float v[32];
; #pragma unroll
;             for (int n = 0; n < 32; ++n) v[n] = STATE[(size_t)(bh * 32 + n) * 16384 + ed];
;             float run = 0.f;
; #pragma unroll
;             for (int n = 0; n < 32; ++n) { SPREV[(size_t)(bh * 32 + n) * 16384 + ed] = (bf16_t)(cvtpk(gm * run, 0.f) & 0xffffu); run = run * gC + v[n]; }
	v_mul_f32_e32 v76, v103, v44
	v_mul_f32_e32 v77, v103, v45
	v_cvt_pk_bf16_f32 v78, v76, v77
	global_store_dword v11, v78, s[98:99]
	v_fmac_f32_e32 v46, v2, v44
	v_fmac_f32_e32 v47, v2, v45
	s_add_u32 s98, s98, 0x8000
	s_addc_u32 s99, s99, 0
	v_mul_f32_e32 v76, v103, v46
	v_mul_f32_e32 v77, v103, v47
	v_cvt_pk_bf16_f32 v79, v76, v77
	global_store_dword v11, v79, s[98:99]
	v_fmac_f32_e32 v48, v2, v46
	v_fmac_f32_e32 v49, v2, v47
	s_add_u32 s98, s98, 0x8000
	s_addc_u32 s99, s99, 0
	v_mul_f32_e32 v76, v103, v48
	v_mul_f32_e32 v77, v103, v49
	v_cvt_pk_bf16_f32 v78, v76, v77
	global_store_dword v11, v78, s[98:99]
	v_fmac_f32_e32 v50, v2, v48
	v_fmac_f32_e32 v51, v2, v49
	s_add_u32 s98, s98, 0x8000
	s_addc_u32 s99, s99, 0
	v_mul_f32_e32 v76, v103, v50
	v_mul_f32_e32 v77, v103, v51
	v_cvt_pk_bf16_f32 v79, v76, v77
	global_store_dword v11, v79, s[98:99]
	v_fmac_f32_e32 v52, v2, v50
	v_fmac_f32_e32 v53, v2, v51
	s_add_u32 s98, s98, 0x8000
	s_addc_u32 s99, s99, 0
	v_mul_f32_e32 v76, v103, v52
	v_mul_f32_e32 v77, v103, v53
	v_cvt_pk_bf16_f32 v78, v76, v77
	global_store_dword v11, v78, s[98:99]
	v_fmac_f32_e32 v54, v2, v52
	v_fmac_f32_e32 v55, v2, v53
	s_add_u32 s98, s98, 0x8000
	s_addc_u32 s99, s99, 0
	v_mul_f32_e32 v76, v103, v54
	v_mul_f32_e32 v77, v103, v55
	v_cvt_pk_bf16_f32 v79, v76, v77
	global_store_dword v11, v79, s[98:99]
	v_fmac_f32_e32 v56, v2, v54
	v_fmac_f32_e32 v57, v2, v55
	s_add_u32 s98, s98, 0x8000
	s_addc_u32 s99, s99, 0
	v_mul_f32_e32 v76, v103, v56
	v_mul_f32_e32 v77, v103, v57
	v_cvt_pk_bf16_f32 v78, v76, v77
	global_store_dword v11, v78, s[98:99]
	v_fmac_f32_e32 v58, v2, v56
	v_fmac_f32_e32 v59, v2, v57
	s_add_u32 s98, s98, 0x8000
	s_addc_u32 s99, s99, 0
	v_mul_f32_e32 v76, v103, v58
	v_mul_f32_e32 v77, v103, v59
	v_cvt_pk_bf16_f32 v79, v76, v77
	global_store_dword v11, v79, s[98:99]
	v_fmac_f32_e32 v60, v2, v58
	v_fmac_f32_e32 v61, v2, v59
	s_add_u32 s98, s98, 0x8000
	s_addc_u32 s99, s99, 0
	v_mul_f32_e32 v76, v103, v60
	v_mul_f32_e32 v77, v103, v61
	v_cvt_pk_bf16_f32 v78, v76, v77
	global_store_dword v11, v78, s[98:99]
	v_fmac_f32_e32 v62, v2, v60
	v_fmac_f32_e32 v63, v2, v61
	s_add_u32 s98, s98, 0x8000
	s_addc_u32 s99, s99, 0
	v_mul_f32_e32 v76, v103, v62
	v_mul_f32_e32 v77, v103, v63
	v_cvt_pk_bf16_f32 v79, v76, v77
	global_store_dword v11, v79, s[98:99]
	v_fmac_f32_e32 v64, v2, v62
	v_fmac_f32_e32 v65, v2, v63
	s_add_u32 s98, s98, 0x8000
	s_addc_u32 s99, s99, 0
	v_mul_f32_e32 v76, v103, v64
	v_mul_f32_e32 v77, v103, v65
	v_cvt_pk_bf16_f32 v78, v76, v77
	global_store_dword v11, v78, s[98:99]
	v_fmac_f32_e32 v66, v2, v64
	v_fmac_f32_e32 v67, v2, v65
	s_add_u32 s98, s98, 0x8000
	s_addc_u32 s99, s99, 0
	v_mul_f32_e32 v76, v103, v66
	v_mul_f32_e32 v77, v103, v67
	v_cvt_pk_bf16_f32 v79, v76, v77
	global_store_dword v11, v79, s[98:99]
	v_fmac_f32_e32 v68, v2, v66
	v_fmac_f32_e32 v69, v2, v67
	s_add_u32 s98, s98, 0x8000
	s_addc_u32 s99, s99, 0
	v_mul_f32_e32 v76, v103, v68
	v_mul_f32_e32 v77, v103, v69
	v_cvt_pk_bf16_f32 v78, v76, v77
	global_store_dword v11, v78, s[98:99]
	v_fmac_f32_e32 v70, v2, v68
	v_fmac_f32_e32 v71, v2, v69
	s_add_u32 s98, s98, 0x8000
	s_addc_u32 s99, s99, 0
	v_mul_f32_e32 v76, v103, v70
	v_mul_f32_e32 v77, v103, v71
	v_cvt_pk_bf16_f32 v79, v76, v77
	global_store_dword v11, v79, s[98:99]
	v_fmac_f32_e32 v72, v2, v70
	v_fmac_f32_e32 v73, v2, v71
	s_add_u32 s98, s98, 0x8000
	s_addc_u32 s99, s99, 0
	v_mul_f32_e32 v76, v103, v72
	v_mul_f32_e32 v77, v103, v73
	v_cvt_pk_bf16_f32 v78, v76, v77
	global_store_dword v11, v78, s[98:99]
	v_fmac_f32_e32 v74, v2, v72
	v_fmac_f32_e32 v75, v2, v73
	s_add_u32 s98, s98, 0x8000
	s_addc_u32 s99, s99, 0
	v_mul_f32_e32 v76, v103, v74
	v_mul_f32_e32 v77, v103, v75
	v_cvt_pk_bf16_f32 v79, v76, v77
	global_store_dword v11, v79, s[98:99]
